# v34 plus q/k pair loop prefetches the next pair's source loads during the current pair's arithmetic
# baseline (speedup 1.0000x reference)
; __device__ __forceinline__ void ew_phase(const Params& p, int l) {
;     ...
;         const int t = tid & 15; const long grp = ((long)blockIdx.x * NTHREADS + tid) >> 4, ngrp = (long)gridDim.x * NTHREADS / 16;
;         const float2* rope = (const float2*)(ws + WS_ROPE);
;         const int base = ((t & 8) ? 64 : 0) + 4 * (t & 7), fi = 4 * (t & 7);
;         bf16_t* KC = (bf16_t*)(ws + WS_KC);
; #pragma unroll 2
;         for (long it = grp; it < (long)ROWS * 20; it += ngrp) { const int row = (int)(it / 20), head = (int)(it % 20);
;             const bf16_t* src_ = P + (size_t)row * INC + (head < 16 ? OQ + head * 128 : OKK + (head - 16) * 128) + base;
;             bf16_t* dst_ = (head < 16) ? (P + (size_t)row * INC + OQ + head * 128 + base) : (KC + ((size_t)(head - 16) * ROWS + row) * 128 + base);
;             const float* gn = (head < 16 ? p.in[I_QN] : p.in[I_KN]) + (size_t)l * 128 + base;
;             const u32x2 wa = *(const u32x2*)src_, wb = *(const u32x2*)(src_ + 32);
.LBB0_244:
	s_andn2_b64 vcc, exec, s[0:1]
	s_cbranch_vccnz .LBB0_282
	s_cmp_gt_i32 s46, 5
	s_mov_b64 s[0:1], -1
	s_cbranch_scc0 .LBB0_266
	v_mov_b32_e32 v0, v190
	v_readlane_b32 s0, v246, 21
	v_readlane_b32 s1, v246, 22
	v_ashrrev_i32_e32 v1, 31, v0
	s_mov_b32 s21, s86
	v_lshl_add_u64 v[114:115], s[0:1], 0, v[0:1]
	v_ashrrev_i64 v[2:3], 4, v[114:115]
	s_mov_b64 s[0:1], 0x29400
	s_mov_b32 s20, s85
	v_cmp_gt_i64_e32 vcc, s[0:1], v[2:3]
	s_and_saveexec_b64 s[4:5], vcc
	s_cbranch_execz .LBB0_253
	v_lshlrev_b32_e32 v5, 2, v0
	v_and_b32_e32 v5, 28, v5
	v_and_b32_e32 v4, 8, v0
	v_and_b32_e32 v6, 64, v191
	v_lshlrev_b32_e32 v96, 3, v5
	v_cmp_eq_u32_e32 vcc, 0, v4
	v_lshl_or_b32 v4, v4, 3, v5
	v_add_u32_e32 v8, 64, v6
	v_lshl_add_u64 v[6:7], s[54:55], 0, v[96:97]
	s_mov_b64 s[0:1], 0x1c8f0000
	v_xor_b32_e32 v5, 8, v191
	v_lshl_add_u64 v[6:7], v[6:7], 0, s[0:1]
	v_cmp_lt_i32_e64 s[0:1], v5, v8
	v_xor_b32_e32 v9, 4, v191
	v_xor_b32_e32 v10, 2, v191
	v_cndmask_b32_e64 v5, v191, v5, s[0:1]
	v_cmp_lt_i32_e64 s[0:1], v9, v8
	v_lshlrev_b32_e32 v5, 2, v5
	s_mov_b64 s[14:15], 0
	v_cndmask_b32_e64 v9, v191, v9, s[0:1]
	v_cmp_lt_i32_e64 s[0:1], v10, v8
	v_lshlrev_b32_e32 v9, 2, v9
	s_nop 0
	v_cndmask_b32_e64 v10, v191, v10, s[0:1]
	v_lshlrev_b32_e32 v26, 2, v10
	v_xor_b32_e32 v10, 1, v191
	v_cmp_lt_i32_e64 s[0:1], v10, v8
	s_nop 1
	v_cndmask_b32_e64 v8, v191, v10, s[0:1]
	v_readlane_b32 s0, v246, 23
	v_lshlrev_b32_e32 v27, 2, v8
	v_lshlrev_b64 v[2:3], 1, v[2:3]
	v_lshlrev_b32_e32 v8, 7, v2
	s_lshl_b32 s18, s0, 8
	v_readlane_b32 s1, v246, 24
	v_mov_b32_e32 v130, v2
	s_mov_b32 s99, 0xcccccccd
	v_mul_hi_u32 v131, v130, s99
	v_lshrrev_b32_e32 v131, 4, v131
	v_lshlrev_b32_e32 v132, 7, v130
	v_mul_u32_u24_e32 v135, 0xa00, v131
	v_sub_u32_e32 v132, v132, v135
	v_mul_u32_u24_e32 v135, 0x8800, v131
	v_add_u32_e32 v132, v132, v4
	v_lshl_add_u32 v136, v132, 1, v135
	v_mov_b32_e32 v137, 0
	v_lshl_add_u64 v[136:137], s[8:9], 0, v[136:137]
	flat_load_dwordx2 v[86:87], v[136:137]
	flat_load_dwordx2 v[88:89], v[136:137] offset:64
	flat_load_dwordx2 v[90:91], v[136:137] offset:256
	flat_load_dwordx2 v[92:93], v[136:137] offset:320
	s_branch .LBB0_249

; __device__ __forceinline__ float bflo(unsigned w) { return __uint_as_float(w << 16); }
; __device__ __forceinline__ float bfhi(unsigned w) { return __uint_as_float(w & 0xffff0000u); }
; __device__ __forceinline__ void ew_phase(const Params& p, int l) {
;     ...
;         for (long it = grp; it < (long)ROWS * 20; it += ngrp) { const int row = (int)(it / 20), head = (int)(it % 20);
;             const bf16_t* src_ = P + (size_t)row * INC + (head < 16 ? OQ + head * 128 : OKK + (head - 16) * 128) + base;
;             bf16_t* dst_ = (head < 16) ? (P + (size_t)row * INC + OQ + head * 128 + base) : (KC + ((size_t)(head - 16) * ROWS + row) * 128 + base);
;             const float* gn = (head < 16 ? p.in[I_QN] : p.in[I_KN]) + (size_t)l * 128 + base;
;             const u32x2 wa = *(const u32x2*)src_, wb = *(const u32x2*)(src_ + 32);
;             const f32x4 ga = *(const f32x4*)gn, gb = *(const f32x4*)(gn + 32);
;             float a[4] = {bflo(wa.x), bfhi(wa.x), bflo(wa.y), bfhi(wa.y)}, b[4] = {bflo(wb.x), bfhi(wb.x), bflo(wb.y), bfhi(wb.y)};
;             float ss = 0.f;
; #pragma unroll
;             for (int q = 0; q < 4; ++q) ss += a[q] * a[q] + b[q] * b[q];
; #pragma unroll
;             for (int o = 8; o >= 1; o >>= 1) ss += __shfl_xor(ss, o);
.LBB0_251:
	s_or_b64 exec, exec, s[16:17]
	v_readlane_b32 s0, v245, 45
	v_lshlrev_b32_e32 v96, 1, v4
	v_readlane_b32 s1, v245, 46
	v_lshl_add_u64 v[14:15], v[14:15], 0, v[96:97]
	s_nop 0
	v_lshl_add_u64 v[16:17], v[18:19], 0, s[0:1]
	v_lshlrev_b32_e32 v18, 2, v4
	v_mov_b32_e32 v19, v97
	v_lshl_add_u64 v[16:17], v[16:17], 0, v[18:19]
	global_load_dwordx4 v[28:31], v[16:17], off
	global_load_dwordx4 v[32:35], v[16:17], off offset:128
	global_load_dwordx4 v[228:231], v[16:17], off
	global_load_dwordx4 v[232:235], v[16:17], off offset:128
	s_mov_b64 s[98:99], 0x13ff
	v_cmp_lt_i64_e64 s[98:99], s[98:99], v[2:3]
	s_and_saveexec_b64 s[100:101], s[98:99]
	v_add_u32_e32 v209, 0xffffff00, v12
	v_and_b32_e32 v208, 63, v12
	v_lshrrev_b32_e32 v209, 6, v209
	v_cndmask_b32_e32 v208, v208, v209, vcc
	v_lshlrev_b32_e32 v208, 5, v208
	v_mov_b32_e32 v209, v97
	v_lshl_add_u64 v[208:209], v[208:209], 3, v[6:7]
	flat_load_dwordx4 v[200:203], v[208:209]
	flat_load_dwordx4 v[204:207], v[208:209] offset:16
	flat_load_dwordx4 v[120:123], v[208:209]
	flat_load_dwordx4 v[124:127], v[208:209] offset:16
	s_mov_b64 exec, s[100:101]
	s_mov_b32 s0, 0x800000
	s_waitcnt vmcnt(0) lgkmcnt(0)
	v_mov_b32_e32 v18, v86
	v_mov_b32_e32 v19, v87
	v_mov_b32_e32 v14, v88
	v_mov_b32_e32 v15, v89
	v_mov_b32_e32 v218, v90
	v_mov_b32_e32 v219, v91
	v_mov_b32_e32 v214, v92
	v_mov_b32_e32 v215, v93
	v_readlane_b32 s98, v246, 23
	s_nop 3
	s_lshl_b32 s98, s98, 1
	v_add_u32_e32 v130, s98, v2
	v_min_u32_e32 v130, 0x293fe, v130
	s_mov_b32 s99, 0xcccccccd
	v_mul_hi_u32 v131, v130, s99
	v_lshrrev_b32_e32 v131, 4, v131
	v_lshlrev_b32_e32 v132, 7, v130
	v_mul_u32_u24_e32 v135, 0xa00, v131
	v_sub_u32_e32 v132, v132, v135
	v_mul_u32_u24_e32 v135, 0x8800, v131
	v_add_u32_e32 v132, v132, v4
	v_lshl_add_u32 v136, v132, 1, v135
	v_mov_b32_e32 v137, 0
	v_lshl_add_u64 v[136:137], s[8:9], 0, v[136:137]
	flat_load_dwordx2 v[86:87], v[136:137]
	flat_load_dwordx2 v[88:89], v[136:137] offset:64
	flat_load_dwordx2 v[90:91], v[136:137] offset:256
	flat_load_dwordx2 v[92:93], v[136:137] offset:320
	v_lshlrev_b32_e32 v20, 16, v18
	v_and_b32_e32 v21, 0xffff0000, v14
	v_lshlrev_b32_e32 v16, 16, v14
	v_and_b32_e32 v17, 0xffff0000, v18
	v_pk_mul_f32 v[24:25], v[20:21], v[20:21]
	v_lshlrev_b32_e32 v38, 16, v15
	v_and_b32_e32 v39, 0xffff0000, v19
	v_pk_fma_f32 v[24:25], v[16:17], v[16:17], v[24:25]
	v_lshlrev_b32_e32 v14, 16, v19
	v_and_b32_e32 v15, 0xffff0000, v15
	v_pk_mul_f32 v[18:19], v[38:39], v[38:39]
	v_add_f32_e32 v13, v24, v25
	v_pk_fma_f32 v[18:19], v[14:15], v[14:15], v[18:19]
	v_mov_b32_e32 v22, v16
	v_add_f32_e32 v13, v18, v13
	v_add_f32_e32 v13, v19, v13
	ds_bpermute_b32 v18, v5, v13
	v_mov_b32_e32 v23, v21
	v_mov_b32_e32 v36, v32
	v_mov_b32_e32 v37, v29
	v_mov_b32_e32 v29, v33
	s_waitcnt lgkmcnt(0)
	v_add_f32_e32 v13, v13, v18
	ds_bpermute_b32 v18, v9, v13
	v_mov_b32_e32 v40, v38
	v_mov_b32_e32 v41, v15
	s_waitcnt lgkmcnt(0)
	v_add_f32_e32 v13, v13, v18
	ds_bpermute_b32 v18, v26, v13
	s_waitcnt lgkmcnt(0)
	v_add_f32_e32 v13, v13, v18
	ds_bpermute_b32 v18, v27, v13
	s_waitcnt lgkmcnt(0)
	v_add_f32_e32 v13, v13, v18
	v_fmamk_f32 v13, v13, 0x3c000000, v193
	v_cmp_gt_f32_e64 s[0:1], s0, v13
	v_mul_f32_e32 v18, 0x4b800000, v13
	s_nop 0
	v_cndmask_b32_e64 v13, v13, v18, s[0:1]
	v_rsq_f32_e32 v13, v13
	s_nop 0
	v_mul_f32_e32 v18, 0x45800000, v13
	v_cndmask_b32_e64 v24, v13, v18, s[0:1]
	v_pk_mul_f32 v[18:19], v[24:25], v[20:21] op_sel_hi:[0,1]
	v_pk_mul_f32 v[16:17], v[24:25], v[16:17] op_sel_hi:[0,1]
	v_pk_mul_f32 v[42:43], v[24:25], v[22:23] op_sel_hi:[0,1]
	v_pk_mul_f32 v[22:23], v[36:37], v[16:17]
	v_pk_mul_f32 v[20:21], v[28:29], v[18:19]
	v_pk_mul_f32 v[14:15], v[24:25], v[14:15] op_sel_hi:[0,1]
	v_pk_mul_f32 v[16:17], v[24:25], v[38:39] op_sel_hi:[0,1]
	v_pk_mul_f32 v[24:25], v[24:25], v[40:41] op_sel_hi:[0,1]
	v_mov_b32_e32 v28, v34
	v_mov_b32_e32 v29, v31
	v_mov_b32_e32 v31, v35
	s_mov_b64 s[0:1], 0x13ff
	v_pk_mul_f32 v[18:19], v[32:33], v[42:43]
	v_pk_mul_f32 v[16:17], v[28:29], v[16:17]
	v_pk_mul_f32 v[14:15], v[30:31], v[14:15]
	v_pk_mul_f32 v[24:25], v[34:35], v[24:25]
	v_cmp_lt_i64_e64 s[0:1], s[0:1], v[2:3]
	s_and_saveexec_b64 s[16:17], s[0:1]
	s_cbranch_execz .LBB0_248
	v_mov_b32_e32 v36, v22
	v_mov_b32_e32 v37, v21
	v_mov_b32_e32 v18, v20
	v_mov_b32_e32 v19, v23
	v_mov_b32_e32 v24, v14
	v_mov_b32_e32 v25, v17
	s_waitcnt vmcnt(0) lgkmcnt(0)
	v_mov_b32_e32 v38, v201
	v_mov_b32_e32 v39, v203
	v_mov_b32_e32 v12, v200
	v_mov_b32_e32 v13, v202
	v_pk_mul_f32 v[36:37], v[36:37], v[38:39]
	s_nop 0
	v_pk_fma_f32 v[12:13], v[18:19], v[12:13], v[36:37] neg_lo:[0,0,1] neg_hi:[0,0,1]
	v_mov_b32_e32 v18, v200
	v_mov_b32_e32 v19, v203
	v_pk_mul_f32 v[18:19], v[22:23], v[18:19]
	v_mov_b32_e32 v22, v201
	v_mov_b32_e32 v23, v202
	v_pk_fma_f32 v[18:19], v[20:21], v[22:23], v[18:19]
	v_mov_b32_e32 v22, v16
	v_mov_b32_e32 v23, v15
	v_mov_b32_e32 v200, v205
	v_mov_b32_e32 v201, v207
	v_mov_b32_e32 v20, v204
	v_mov_b32_e32 v21, v206
	v_pk_mul_f32 v[22:23], v[22:23], v[200:201]
	s_nop 0
	v_pk_fma_f32 v[200:201], v[24:25], v[20:21], v[22:23] neg_lo:[0,0,1] neg_hi:[0,0,1]
	v_mov_b32_e32 v21, v207
	v_pk_mul_f32 v[16:17], v[16:17], v[20:21]
	v_mov_b32_e32 v20, v205
	v_mov_b32_e32 v21, v206
	v_pk_fma_f32 v[24:25], v[14:15], v[20:21], v[16:17]
	v_mov_b32_e32 v20, v12
	v_mov_b32_e32 v23, v13
	v_mov_b32_e32 v14, v200
	v_mov_b32_e32 v17, v201
	s_branch .LBB0_248
